# e29: as e28b but no lane swaps: out_proj stages out_w without the row permutation (one set-up instruction), accumulators leave the K loop in the 64B-contiguous column layout
# baseline (speedup 1.0000x reference)
; #define PG8_STAGE_A(bufoff, gbase) PG8_STAGE(bufoff, gbase, voffA, a64)
; #define PG8_STAGE_B(bufoff, bp, hb, tz) do { if (BMODE == 1 && (tz)) PG8_STAGE(bufoff, (bp) + (hb) * 4096, voffT, t64); else PG8_STAGE(bufoff, (bp) + (hb) * bhstep, voffB, b64); } while (0)
; #define PG8_WAIT_V(n) asm volatile("s_waitcnt vmcnt(" #n ")" ::: "memory")
; #define PG8_BAR __builtin_amdgcn_s_barrier()
; template <class CF, class Epi, class Sched, bool ALIGN_EPI, bool SP2>
; __device__ __forceinline__ void gemm_phase(LAS unsigned char* lds, const char* gA, const char* gB, const Sched& S, const Epi& E, const char* gB2 = nullptr) {
;     ...
;     { int R, C; stage_rc(tid * 16, R, C); const int Rb = Epi::PERM ? ((R & ~31) + perm32(R & 31)) : R;
;       voffA = AMODE == 0 ? (unsigned)R * CF::A_ROW + (unsigned)C * 2u : (unsigned)(C >> 4) * CF::A_ROW + (unsigned)R * 32u + (unsigned)(C & 15) * 2u;
;       voffB = (unsigned)Rb * CF::B_ROW + (unsigned)C * 2u;
;     ...
;     const char* cA = gA + (size_t)cur.g * CF::A_G + (size_t)cur.pm * CF::A_T; const char* cB = gB + (size_t)cur.g * CF::B_G + (size_t)cur.pn * CF::B_T;
;     const char* cT = BMODE == 1 ? gB2 + (size_t)cur.g * KTG + (size_t)cur.pn * 8192 + 14336 : nullptr;
;     PG8_STAGE_B(PG8_SB(0, 0), cB, 0, false); PG8_STAGE_B(PG8_SB(0, 1), cB, 1, false); PG8_STAGE_A(PG8_SA(0, 0), cA); PG8_STAGE_A(PG8_SA(0, 1), cA + ahstep);
;     if (wr == 1) PG8_BAR;
;     PG8_WAIT_V(2); PG8_BAR;
;     PG8_STAGE_B(PG8_SB(1, 0), cB + bkstep, 0, false); PG8_STAGE_A(PG8_SA(1, 0), cA + akstep); PG8_STAGE_B(PG8_SB(1, 1), cB + bkstep, 1, false);
;     PG8_WAIT_V(6); PG8_BAR;
.LBB0_1138:
	s_andn2_b64 vcc, exec, s[2:3]
	s_cbranch_vccnz .LBB0_1174
	v_and_b32_e32 v252, 15, v0
	v_lshrrev_b32_e32 v253, 8, v0
	v_lshl_or_b32 v252, v253, 6, v252
	v_bfe_u32 v253, v0, 6, 2
	v_bfe_u32 v251, v0, 4, 2
	v_lshlrev_b32_e32 v251, 2, v251
	v_lshl_or_b32 v253, v253, 5, v251
	v_lshl_add_u32 v250, s58, 8, v252
	v_lshl_or_b32 v251, s22, 8, v253
	v_readlane_b32 s98, v254, 2
	v_readlane_b32 s99, v254, 3
	v_lshlrev_b32_e32 v250, 13, v250
	v_lshlrev_b32_e32 v251, 2, v251
	s_cmp_gt_i32 s58, 31
	s_cselect_b32 vcc_lo, 0x6000, 0
	s_add_u32 s100, s50, vcc_lo
	s_addc_u32 s101, s51, 0
	s_add_u32 s100, s100, 0x104000
	s_addc_u32 s101, s101, 0
	v_add_u32_e32 v250, v250, v251
	s_nop 1
	global_load_dwordx4 v[218:221], v251, s[100:101]
	global_load_dwordx4 v[222:225], v251, s[100:101] offset:64
	global_load_dwordx4 v[226:229], v251, s[100:101] offset:512
	global_load_dwordx4 v[230:233], v251, s[100:101] offset:576
	global_load_dwordx4 v[234:237], v250, s[98:99] nt
	global_load_dwordx4 v[238:241], v250, s[98:99] offset:64 nt
	global_load_dwordx4 v[242:245], v250, s[98:99] offset:512 nt
	global_load_dwordx4 v[246:249], v250, s[98:99] offset:576 nt
	s_add_u32 s0, s50, 0x19800000
	s_addc_u32 s1, s51, 0
	s_add_u32 s33, s50, 0x1400000
	s_addc_u32 s64, s51, 0
	s_lshr_b32 s3, s18, 6
	s_ashr_i32 s59, s58, 31
	s_lshr_b32 s2, s18, 8
	s_lshl_b32 s65, s3, 10
	s_lshl_b64 s[4:5], s[58:59], 20
	v_lshlrev_b32_e32 v2, 4, v0
	v_and_b32_e32 v3, 32, v0
	v_lshrrev_b32_e32 v4, 3, v0
	v_bfe_u32 v1, v0, 2, 4
	s_add_u32 s20, s0, s4
	v_and_or_b32 v5, v4, 48, v1
	v_bitop3_b32 v6, v2, v3, 48 bitop3:0x6c
	v_and_b32_e32 v3, 32, v4
	v_lshrrev_b32_e32 v4, 1, v0
	v_lshrrev_b32_e32 v8, 5, v0
	v_bfe_u32 v9, v0, 2, 2
	s_addc_u32 s21, s1, s5
	s_ashr_i32 s23, s22, 31
	v_and_b32_e32 v7, 64, v0
	v_and_b32_e32 v4, 24, v4
	v_and_or_b32 v8, v8, 4, v9
	s_lshl_b64 s[4:5], s[22:23], 20
	v_or_b32_e32 v2, v6, v7
	v_or3_b32 v3, v8, v3, v4
	s_add_u32 s62, s33, s4
	v_lshl_or_b32 v162, v5, 12, v2
	s_addc_u32 s63, s64, s5
	v_mov_b32_e32 v163, 0
	s_add_i32 s66, s65, 0
	v_lshl_or_b32 v160, v5, 12, v2
	v_lshl_add_u64 v[2:3], s[62:63], 0, v[162:163]
	s_add_i32 m0, s66, 0x10000
	s_mov_b64 s[8:9], 0x40000
	global_load_lds_dwordx4 v162, s[62:63]
	v_lshl_add_u64 v[4:5], v[2:3], 0, s[8:9]
	s_add_i32 m0, s66, 0x12000
	s_mov_b64 s[10:11], 0x80000
	global_load_lds_dwordx4 v[4:5], off
	v_lshl_add_u64 v[4:5], v[2:3], 0, s[10:11]
	s_add_i32 m0, s66, 0x14000
	s_mov_b64 s[12:13], 0xc0000
	global_load_lds_dwordx4 v[4:5], off
	v_lshl_add_u64 v[4:5], v[2:3], 0, s[12:13]
	s_add_i32 m0, s66, 0x16000
	v_mov_b32_e32 v161, v163
	global_load_lds_dwordx4 v[4:5], off
	v_lshl_add_u64 v[4:5], s[20:21], 0, v[160:161]
	s_mov_b32 m0, s66
	s_add_i32 s67, s66, 0x2000
	global_load_lds_dwordx4 v160, s[20:21]
	v_lshl_add_u64 v[8:9], v[4:5], 0, s[8:9]
	s_mov_b32 m0, s67
	s_add_i32 s68, s66, 0x4000
	global_load_lds_dwordx4 v[8:9], off
	v_lshl_add_u64 v[8:9], v[4:5], 0, s[10:11]
	s_mov_b32 m0, s68
	s_add_i32 s69, s66, 0x6000
	global_load_lds_dwordx4 v[8:9], off
	v_lshl_add_u64 v[8:9], v[4:5], 0, s[12:13]
	s_mov_b32 m0, s69
	v_writelane_b32 v254, s82, 18
	global_load_lds_dwordx4 v[8:9], off
	s_nop 0
	v_writelane_b32 v254, s83, 19
	s_cmp_eq_u32 s2, 1
	s_mov_b32 s96, s53
	s_mov_b32 s53, s81
	v_writelane_b32 v254, s78, 36
	s_cselect_b64 s[14:15], -1, 0
	s_cmp_lg_u32 s2, 1
	s_mov_b32 s23, 0
	v_writelane_b32 v254, s79, 37
	s_cbranch_scc1 .LBB0_1141
	s_barrier

; __device__ __forceinline__ f32x4 ld_nt(const float* p) { return __builtin_nontemporal_load((const f32x4*)p); }
; __device__ __forceinline__ u32x4 pack8h(const f32x4 v0, const f32x4 v1) { u32x4 w; w.x = pk_h16(v0[0], v0[1]); w.y = pk_h16(v0[2], v0[3]); w.z = pk_h16(v1[0], v1[1]); w.w = pk_h16(v1[2], v1[3]); return w; }
;     __device__ __forceinline__ void operator()(AccRef acc, const Unit& u, int wr, int wc, int fr, int fq) const {
;     ...
;                         for (int n = 0; n < 2; ++n) xv[mm][bj][n] = ld_nt(x + (size_t)(row0 + ai * HALF + (mp * 2 + mm) * 16) * D + col0 + bj * HALF + n * 4);
;                 __builtin_amdgcn_sched_barrier(0);
; #pragma unroll
;                 for (int mm = 0; mm < 2; ++mm) { const int m = mp * 2 + mm; const int row = row0 + ai * HALF + m * 16; const size_t o = (size_t)row * D + col0; float ss = 0.f;
; #pragma unroll
;                     for (int bj = 0; bj < 2; ++bj) { const f32x4 r0 = xv[mm][bj][0] + gv[bj][0] * acc[ai][bj][m][0], r1 = xv[mm][bj][1] + gv[bj][1] * acc[ai][bj][m][1];
;                         *(u32x4*)(xo + o + bj * HALF) = pack8h(r0, r1);
;                         ss += ((r0[0] * r0[0] + r0[1] * r0[1]) + (r0[2] * r0[2] + r0[3] * r0[3])) + ((r1[0] * r1[0] + r1[1] * r1[1]) + (r1[2] * r1[2] + r1[3] * r1[3])); }
.LBB0_1154:
	v_lshl_add_u32 v172, s58, 8, v178
	v_lshrrev_b32_e32 v170, 4, v184
	v_and_b32_e32 v171, 0x60, v180
	v_lshl_or_b32 v170, v170, 2, v171
	v_lshl_or_b32 v170, s22, 8, v170
	v_readlane_b32 s80, v254, 2
	v_readlane_b32 s81, v254, 3
	v_lshlrev_b32_e32 v173, 13, v172
	v_lshlrev_b32_e32 v187, 7, v172
	v_lshlrev_b32_e32 v171, 2, v170
	v_lshl_add_u32 v173, v170, 2, v173
	s_lshl_b32 s18, s22, 2
	s_add_u32 s18, s18, s72
	s_lshl_b32 s18, s18, 2
	s_add_u32 s88, s26, s18
	s_addc_u32 s89, s27, 0
	v_xor_b32_e32 v186, 16, v184
	v_xor_b32_e32 v185, 32, v184
	v_lshrrev_b32_e32 v174, 4, v184
	v_lshlrev_b32_e32 v186, 2, v186
	v_lshlrev_b32_e32 v185, 2, v185
	v_lshl_add_u32 v174, v174, 4, v187
	s_mov_b32 s94, 0x3a000000
	s_mov_b32 s95, 0x358637bd
	s_mov_b64 s[82:83], s[48:49]
	s_lshr_b32 s59, s65, 10
	global_load_dwordx4 v[144:147], v171, s[46:47]
	global_load_dwordx4 v[148:151], v171, s[46:47] offset:64
	global_load_dwordx4 v[152:155], v171, s[46:47] offset:512
	global_load_dwordx4 v[156:159], v171, s[46:47] offset:576
	s_add_u32 s84, s80, 0x20000
	s_addc_u32 s85, s81, 0
	global_load_dwordx4 v[188:191], v173, s[84:85] nt
	global_load_dwordx4 v[192:195], v173, s[84:85] offset:64 nt
	global_load_dwordx4 v[196:199], v173, s[84:85] offset:512 nt
	global_load_dwordx4 v[200:203], v173, s[84:85] offset:576 nt
	s_add_u32 s84, s80, 0x40000
	s_addc_u32 s85, s81, 0
	global_load_dwordx4 v[104:107], v173, s[84:85] nt
	global_load_dwordx4 v[108:111], v173, s[84:85] offset:64 nt
	global_load_dwordx4 v[112:115], v173, s[84:85] offset:512 nt
	global_load_dwordx4 v[120:123], v173, s[84:85] offset:576 nt
	s_waitcnt vmcnt(12)
	v_pk_fma_f32 v[140:141], v[140:141], v[218:219], v[234:235]
	v_pk_fma_f32 v[142:143], v[142:143], v[220:221], v[236:237]
	v_pk_fma_f32 v[136:137], v[136:137], v[222:223], v[238:239]
	v_pk_fma_f32 v[138:139], v[138:139], v[224:225], v[240:241]
	v_pk_fma_f32 v[132:133], v[132:133], v[226:227], v[242:243]
	v_pk_fma_f32 v[134:135], v[134:135], v[228:229], v[244:245]
	v_pk_fma_f32 v[128:129], v[128:129], v[230:231], v[246:247]
	v_pk_fma_f32 v[130:131], v[130:131], v[232:233], v[248:249]
	s_add_u32 s84, s80, 0x60000
	s_addc_u32 s85, s81, 0
	global_load_dwordx4 v[234:237], v173, s[84:85] nt
	global_load_dwordx4 v[238:241], v173, s[84:85] offset:64 nt
	global_load_dwordx4 v[242:245], v173, s[84:85] offset:512 nt
	global_load_dwordx4 v[246:249], v173, s[84:85] offset:576 nt
	v_pk_mul_f32 v[176:177], v[140:141], v[140:141]
	v_pk_fma_f32 v[176:177], v[142:143], v[142:143], v[176:177]
	v_pk_fma_f32 v[176:177], v[136:137], v[136:137], v[176:177]
	v_pk_fma_f32 v[176:177], v[138:139], v[138:139], v[176:177]
	v_pk_fma_f32 v[176:177], v[132:133], v[132:133], v[176:177]
	v_pk_fma_f32 v[176:177], v[134:135], v[134:135], v[176:177]
	v_pk_fma_f32 v[176:177], v[128:129], v[128:129], v[176:177]
	v_pk_fma_f32 v[176:177], v[130:131], v[130:131], v[176:177]
	v_add_f32_e32 v204, v176, v177
	s_waitcnt vmcnt(8)
	v_pk_fma_f32 v[124:125], v[124:125], v[218:219], v[188:189]
	v_pk_fma_f32 v[126:127], v[126:127], v[220:221], v[190:191]
	v_pk_fma_f32 v[116:117], v[116:117], v[222:223], v[192:193]
	v_pk_fma_f32 v[118:119], v[118:119], v[224:225], v[194:195]
	v_pk_fma_f32 v[100:101], v[100:101], v[226:227], v[196:197]
	v_pk_fma_f32 v[102:103], v[102:103], v[228:229], v[198:199]
	v_pk_fma_f32 v[96:97], v[96:97], v[230:231], v[200:201]
	v_pk_fma_f32 v[98:99], v[98:99], v[232:233], v[202:203]
	s_add_u32 s84, s80, 0x100000
	s_addc_u32 s85, s81, 0
	global_load_dwordx4 v[188:191], v173, s[84:85] nt
	global_load_dwordx4 v[192:195], v173, s[84:85] offset:64 nt
	global_load_dwordx4 v[196:199], v173, s[84:85] offset:512 nt
	global_load_dwordx4 v[200:203], v173, s[84:85] offset:576 nt
	v_pk_mul_f32 v[176:177], v[124:125], v[124:125]
	v_pk_fma_f32 v[176:177], v[126:127], v[126:127], v[176:177]
	v_pk_fma_f32 v[176:177], v[116:117], v[116:117], v[176:177]
	v_pk_fma_f32 v[176:177], v[118:119], v[118:119], v[176:177]
	v_pk_fma_f32 v[176:177], v[100:101], v[100:101], v[176:177]
	v_pk_fma_f32 v[176:177], v[102:103], v[102:103], v[176:177]
	v_pk_fma_f32 v[176:177], v[96:97], v[96:97], v[176:177]
	v_pk_fma_f32 v[176:177], v[98:99], v[98:99], v[176:177]
	v_add_f32_e32 v205, v176, v177
	s_waitcnt vmcnt(8)
	v_pk_fma_f32 v[92:93], v[92:93], v[218:219], v[104:105]
	v_pk_fma_f32 v[94:95], v[94:95], v[220:221], v[106:107]
	v_pk_fma_f32 v[88:89], v[88:89], v[222:223], v[108:109]
	v_pk_fma_f32 v[90:91], v[90:91], v[224:225], v[110:111]
	v_pk_fma_f32 v[84:85], v[84:85], v[226:227], v[112:113]
	v_pk_fma_f32 v[86:87], v[86:87], v[228:229], v[114:115]
	v_pk_fma_f32 v[80:81], v[80:81], v[230:231], v[120:121]
	v_pk_fma_f32 v[82:83], v[82:83], v[232:233], v[122:123]
	s_add_u32 s84, s80, 0x120000
	s_addc_u32 s85, s81, 0
	global_load_dwordx4 v[104:107], v173, s[84:85] nt
	global_load_dwordx4 v[108:111], v173, s[84:85] offset:64 nt
	global_load_dwordx4 v[112:115], v173, s[84:85] offset:512 nt
	global_load_dwordx4 v[120:123], v173, s[84:85] offset:576 nt
	v_pk_mul_f32 v[176:177], v[92:93], v[92:93]
	v_pk_fma_f32 v[176:177], v[94:95], v[94:95], v[176:177]
	v_pk_fma_f32 v[176:177], v[88:89], v[88:89], v[176:177]
	v_pk_fma_f32 v[176:177], v[90:91], v[90:91], v[176:177]
	v_pk_fma_f32 v[176:177], v[84:85], v[84:85], v[176:177]
	v_pk_fma_f32 v[176:177], v[86:87], v[86:87], v[176:177]
	v_pk_fma_f32 v[176:177], v[80:81], v[80:81], v[176:177]
	v_pk_fma_f32 v[176:177], v[82:83], v[82:83], v[176:177]
	v_add_f32_e32 v206, v176, v177
	s_waitcnt vmcnt(8)
; __device__ __forceinline__ f32x4 ld_nt(const float* p) { return __builtin_nontemporal_load((const f32x4*)p); }
; __device__ __forceinline__ u32x4 pack8h(const f32x4 v0, const f32x4 v1) { u32x4 w; w.x = pk_h16(v0[0], v0[1]); w.y = pk_h16(v0[2], v0[3]); w.z = pk_h16(v1[0], v1[1]); w.w = pk_h16(v1[2], v1[3]); return w; }
;     __device__ __forceinline__ void operator()(AccRef acc, const Unit& u, int wr, int wc, int fr, int fq) const {
;     ...
;                         for (int n = 0; n < 2; ++n) xv[mm][bj][n] = ld_nt(x + (size_t)(row0 + ai * HALF + (mp * 2 + mm) * 16) * D + col0 + bj * HALF + n * 4);
;                 __builtin_amdgcn_sched_barrier(0);
; #pragma unroll
;                 for (int mm = 0; mm < 2; ++mm) { const int m = mp * 2 + mm; const int row = row0 + ai * HALF + m * 16; const size_t o = (size_t)row * D + col0; float ss = 0.f;
; #pragma unroll
;                     for (int bj = 0; bj < 2; ++bj) { const f32x4 r0 = xv[mm][bj][0] + gv[bj][0] * acc[ai][bj][m][0], r1 = xv[mm][bj][1] + gv[bj][1] * acc[ai][bj][m][1];
;                         *(u32x4*)(xo + o + bj * HALF) = pack8h(r0, r1);
;                         ss += ((r0[0] * r0[0] + r0[1] * r0[1]) + (r0[2] * r0[2] + r0[3] * r0[3])) + ((r1[0] * r1[0] + r1[1] * r1[1]) + (r1[2] * r1[2] + r1[3] * r1[3])); }
;                     ss += __shfl_xor(ss, 16); ss += __shfl_xor(ss, 32);
;                     if (fq == 0) rowss[(size_t)row * 32 + u.pn * 4 + wc] = ss; } }
	v_pk_fma_f32 v[76:77], v[76:77], v[218:219], v[234:235]
	v_pk_fma_f32 v[78:79], v[78:79], v[220:221], v[236:237]
	v_pk_fma_f32 v[72:73], v[72:73], v[222:223], v[238:239]
	v_pk_fma_f32 v[74:75], v[74:75], v[224:225], v[240:241]
	v_pk_fma_f32 v[68:69], v[68:69], v[226:227], v[242:243]
	v_pk_fma_f32 v[70:71], v[70:71], v[228:229], v[244:245]
	v_pk_fma_f32 v[64:65], v[64:65], v[230:231], v[246:247]
	v_pk_fma_f32 v[66:67], v[66:67], v[232:233], v[248:249]
	s_add_u32 s84, s80, 0x140000
	s_addc_u32 s85, s81, 0
	global_load_dwordx4 v[234:237], v173, s[84:85] nt
	global_load_dwordx4 v[238:241], v173, s[84:85] offset:64 nt
	global_load_dwordx4 v[242:245], v173, s[84:85] offset:512 nt
	global_load_dwordx4 v[246:249], v173, s[84:85] offset:576 nt
	v_pk_mul_f32 v[176:177], v[76:77], v[76:77]
	v_pk_fma_f32 v[176:177], v[78:79], v[78:79], v[176:177]
	v_pk_fma_f32 v[176:177], v[72:73], v[72:73], v[176:177]
	v_pk_fma_f32 v[176:177], v[74:75], v[74:75], v[176:177]
	v_pk_fma_f32 v[176:177], v[68:69], v[68:69], v[176:177]
	v_pk_fma_f32 v[176:177], v[70:71], v[70:71], v[176:177]
	v_pk_fma_f32 v[176:177], v[64:65], v[64:65], v[176:177]
	v_pk_fma_f32 v[176:177], v[66:67], v[66:67], v[176:177]
	v_add_f32_e32 v207, v176, v177
	ds_bpermute_b32 v214, v186, v204
	ds_bpermute_b32 v215, v186, v205
	ds_bpermute_b32 v216, v186, v206
	ds_bpermute_b32 v217, v186, v207
	s_waitcnt lgkmcnt(0)
	v_pk_add_f32 v[204:205], v[204:205], v[214:215]
	v_pk_add_f32 v[206:207], v[206:207], v[216:217]
	ds_bpermute_b32 v214, v185, v204
	ds_bpermute_b32 v215, v185, v205
	ds_bpermute_b32 v216, v185, v206
	ds_bpermute_b32 v217, v185, v207
	s_waitcnt lgkmcnt(0)
	v_pk_add_f32 v[204:205], v[204:205], v[214:215]
	v_pk_add_f32 v[206:207], v[206:207], v[216:217]
	s_and_saveexec_b64 s[20:21], s[2:3]
	s_mov_b64 s[90:91], s[88:89]
	global_store_dword v187, v204, s[90:91] sc0 sc1
	s_add_u32 s90, s88, 0x800
	s_addc_u32 s91, s89, 0
	global_store_dword v187, v205, s[90:91] sc0 sc1
	s_add_u32 s90, s88, 0x1000
	s_addc_u32 s91, s89, 0
	global_store_dword v187, v206, s[90:91] sc0 sc1
	s_add_u32 s90, s88, 0x1800
	s_addc_u32 s91, s89, 0
	global_store_dword v187, v207, s[90:91] sc0 sc1
	s_or_b64 exec, exec, s[20:21]
	s_waitcnt vmcnt(12)
	v_pk_fma_f32 v[60:61], v[60:61], v[218:219], v[188:189]
	v_pk_fma_f32 v[62:63], v[62:63], v[220:221], v[190:191]
	v_pk_fma_f32 v[56:57], v[56:57], v[222:223], v[192:193]
	v_pk_fma_f32 v[58:59], v[58:59], v[224:225], v[194:195]
	v_pk_fma_f32 v[52:53], v[52:53], v[226:227], v[196:197]
	v_pk_fma_f32 v[54:55], v[54:55], v[228:229], v[198:199]
	v_pk_fma_f32 v[48:49], v[48:49], v[230:231], v[200:201]
	v_pk_fma_f32 v[50:51], v[50:51], v[232:233], v[202:203]
	s_add_u32 s84, s80, 0x160000
	s_addc_u32 s85, s81, 0
	global_load_dwordx4 v[188:191], v173, s[84:85] nt
	global_load_dwordx4 v[192:195], v173, s[84:85] offset:64 nt
	global_load_dwordx4 v[196:199], v173, s[84:85] offset:512 nt
	global_load_dwordx4 v[200:203], v173, s[84:85] offset:576 nt
	v_pk_mul_f32 v[176:177], v[60:61], v[60:61]
	v_pk_fma_f32 v[176:177], v[62:63], v[62:63], v[176:177]
	v_pk_fma_f32 v[176:177], v[56:57], v[56:57], v[176:177]
	v_pk_fma_f32 v[176:177], v[58:59], v[58:59], v[176:177]
	v_pk_fma_f32 v[176:177], v[52:53], v[52:53], v[176:177]
	v_pk_fma_f32 v[176:177], v[54:55], v[54:55], v[176:177]
	v_pk_fma_f32 v[176:177], v[48:49], v[48:49], v[176:177]
	v_pk_fma_f32 v[176:177], v[50:51], v[50:51], v[176:177]
	v_add_f32_e32 v208, v176, v177
	s_waitcnt vmcnt(12)
	v_pk_fma_f32 v[44:45], v[44:45], v[218:219], v[104:105]
	v_pk_fma_f32 v[46:47], v[46:47], v[220:221], v[106:107]
	v_pk_fma_f32 v[40:41], v[40:41], v[222:223], v[108:109]
	v_pk_fma_f32 v[42:43], v[42:43], v[224:225], v[110:111]
	v_pk_fma_f32 v[36:37], v[36:37], v[226:227], v[112:113]
	v_pk_fma_f32 v[38:39], v[38:39], v[228:229], v[114:115]
	v_pk_fma_f32 v[32:33], v[32:33], v[230:231], v[120:121]
	v_pk_fma_f32 v[34:35], v[34:35], v[232:233], v[122:123]
	v_pk_mul_f32 v[176:177], v[44:45], v[44:45]
	v_pk_fma_f32 v[176:177], v[46:47], v[46:47], v[176:177]
	v_pk_fma_f32 v[176:177], v[40:41], v[40:41], v[176:177]
	v_pk_fma_f32 v[176:177], v[42:43], v[42:43], v[176:177]
	v_pk_fma_f32 v[176:177], v[36:37], v[36:37], v[176:177]
	v_pk_fma_f32 v[176:177], v[38:39], v[38:39], v[176:177]
	v_pk_fma_f32 v[176:177], v[32:33], v[32:33], v[176:177]
	v_pk_fma_f32 v[176:177], v[34:35], v[34:35], v[176:177]
	v_add_f32_e32 v209, v176, v177
	s_waitcnt vmcnt(4)
	v_pk_fma_f32 v[28:29], v[28:29], v[218:219], v[234:235]
	v_pk_fma_f32 v[30:31], v[30:31], v[220:221], v[236:237]
	v_pk_fma_f32 v[24:25], v[24:25], v[222:223], v[238:239]
	v_pk_fma_f32 v[26:27], v[26:27], v[224:225], v[240:241]
	v_pk_fma_f32 v[20:21], v[20:21], v[226:227], v[242:243]
	v_pk_fma_f32 v[22:23], v[22:23], v[228:229], v[244:245]
	v_pk_fma_f32 v[16:17], v[16:17], v[230:231], v[246:247]
	v_pk_fma_f32 v[18:19], v[18:19], v[232:233], v[248:249]
	v_pk_mul_f32 v[176:177], v[28:29], v[28:29]
	v_pk_fma_f32 v[176:177], v[30:31], v[30:31], v[176:177]
	v_pk_fma_f32 v[176:177], v[24:25], v[24:25], v[176:177]
	v_pk_fma_f32 v[176:177], v[26:27], v[26:27], v[176:177]
	v_pk_fma_f32 v[176:177], v[20:21], v[20:21], v[176:177]
	v_pk_fma_f32 v[176:177], v[22:23], v[22:23], v[176:177]
	v_pk_fma_f32 v[176:177], v[16:17], v[16:17], v[176:177]
	v_pk_fma_f32 v[176:177], v[18:19], v[18:19], v[176:177]
	v_add_f32_e32 v210, v176, v177
	s_barrier
	s_cmp_lg_u32 s59, 0
	s_cbranch_scc1 .Lepi_a1
	s_lshl_b32 s18, s58, 6
	s_add_u32 s18, s18, 0xc000
	s_mov_b64 exec, 1
	v_mov_b32_e32 v175, s18
	v_mov_b32_e32 v255, 1
	global_atomic_add v175, v255, s[50:51]
	s_mov_b64 exec, -1
